# prep weight transpose: the 16 row loads of a tile issued together with counted waits before the LDS writes (bit-identical)
# speedup vs baseline: 1.0299x; 1.0138x over previous
.LBB0_31:
	s_lshr_b32 s17, s10, 6
	v_cvt_f32_u32_e32 v7, s17
	s_sub_i32 s20, 0, s17
	s_abs_i32 s19, s16
	s_ashr_i32 s18, s16, 31
	v_rcp_iflag_f32_e32 v7, v7
	s_barrier
	v_mul_f32_e32 v7, 0x4f7ffffe, v7
	v_cvt_u32_f32_e32 v7, v7
	s_nop 0
	v_readfirstlane_b32 s21, v7
	s_mul_i32 s20, s20, s21
	s_mul_hi_u32 s20, s21, s20
	s_add_i32 s21, s21, s20
	s_mul_hi_u32 s20, s19, s21
	s_mul_i32 s21, s20, s17
	s_sub_i32 s19, s19, s21
	s_add_i32 s21, s20, 1
	s_sub_i32 s22, s19, s17
	s_cmp_ge_u32 s19, s17
	s_cselect_b32 s20, s21, s20
	s_cselect_b32 s19, s22, s19
	s_add_i32 s21, s20, 1
	s_cmp_ge_u32 s19, s17
	s_cselect_b32 s19, s21, s20
	s_xor_b32 s19, s19, s18
	s_sub_i32 s18, s19, s18
	s_mul_i32 s17, s18, s17
	s_sub_i32 s16, s16, s17
	s_lshl_b32 s90, s16, 6
	s_ashr_i32 s91, s90, 31
	s_lshl_b32 s94, s18, 6
	s_lshl_b64 s[16:17], s[90:91], 2
	s_add_u32 s16, s92, s16
	s_addc_u32 s17, s93, s17
	v_or_b32_e32 v7, s94, v12
	s_ashr_i32 s95, s94, 31
	v_lshl_add_u64 v[48:49], s[16:17], 0, v[2:3]
	v_mad_u64_u32 v[50:51], s[16:17], v7, s10, 0
	s_mul_i32 s18, s95, s10
	v_add_u32_e32 v51, s18, v51
	v_lshl_add_u64 v[50:51], v[50:51], 2, v[48:49]
	global_load_dword v200, v[50:51], off
	v_or_b32_e32 v54, s90, v13
	v_ashrrev_i32_e32 v55, 31, v54
	v_lshlrev_b64 v[54:55], 11, v[54:55]
	v_or_b32_e32 v7, s94, v14
	v_mad_u64_u32 v[50:51], s[16:17], v7, s10, 0
	v_add_u32_e32 v51, s18, v51
	v_lshl_add_u64 v[50:51], v[50:51], 2, v[48:49]
	global_load_dword v201, v[50:51], off
	v_or_b32_e32 v7, s94, v15
	v_mad_u64_u32 v[50:51], s[16:17], v7, s10, 0
	v_add_u32_e32 v51, s18, v51
	v_lshl_add_u64 v[50:51], v[50:51], 2, v[48:49]
	global_load_dword v202, v[50:51], off
	v_or_b32_e32 v7, s94, v16
	v_mad_u64_u32 v[50:51], s[16:17], v7, s10, 0
	v_add_u32_e32 v51, s18, v51
	v_lshl_add_u64 v[50:51], v[50:51], 2, v[48:49]
	global_load_dword v203, v[50:51], off
	v_or_b32_e32 v7, s94, v17
	v_mad_u64_u32 v[50:51], s[16:17], v7, s10, 0
	v_add_u32_e32 v51, s18, v51
	v_lshl_add_u64 v[50:51], v[50:51], 2, v[48:49]
	global_load_dword v204, v[50:51], off
	v_or_b32_e32 v7, s94, v18
	v_mad_u64_u32 v[50:51], s[16:17], v7, s10, 0
	v_add_u32_e32 v51, s18, v51
	v_lshl_add_u64 v[50:51], v[50:51], 2, v[48:49]
	global_load_dword v205, v[50:51], off
	v_or_b32_e32 v7, s94, v19
	v_mad_u64_u32 v[50:51], s[16:17], v7, s10, 0
	v_add_u32_e32 v51, s18, v51
	v_lshl_add_u64 v[50:51], v[50:51], 2, v[48:49]
	global_load_dword v206, v[50:51], off
	v_or_b32_e32 v7, s94, v20
	v_mad_u64_u32 v[50:51], s[16:17], v7, s10, 0
	v_add_u32_e32 v51, s18, v51
	v_lshl_add_u64 v[50:51], v[50:51], 2, v[48:49]
	global_load_dword v207, v[50:51], off
	v_or_b32_e32 v7, s94, v21
	v_mad_u64_u32 v[50:51], s[16:17], v7, s10, 0
	v_add_u32_e32 v51, s18, v51
	v_lshl_add_u64 v[50:51], v[50:51], 2, v[48:49]
	global_load_dword v208, v[50:51], off
	v_or_b32_e32 v7, s94, v22
	v_mad_u64_u32 v[50:51], s[16:17], v7, s10, 0
	v_add_u32_e32 v51, s18, v51
	v_lshl_add_u64 v[50:51], v[50:51], 2, v[48:49]
	global_load_dword v209, v[50:51], off
	v_or_b32_e32 v7, s94, v23
	v_mad_u64_u32 v[50:51], s[16:17], v7, s10, 0
	v_add_u32_e32 v51, s18, v51
	v_lshl_add_u64 v[50:51], v[50:51], 2, v[48:49]
	global_load_dword v210, v[50:51], off
	v_or_b32_e32 v7, s94, v24
	v_mad_u64_u32 v[50:51], s[16:17], v7, s10, 0
	v_add_u32_e32 v51, s18, v51
	v_lshl_add_u64 v[50:51], v[50:51], 2, v[48:49]
	global_load_dword v211, v[50:51], off
	v_or_b32_e32 v7, s94, v25
	v_mad_u64_u32 v[50:51], s[16:17], v7, s10, 0
	v_add_u32_e32 v51, s18, v51
	v_lshl_add_u64 v[50:51], v[50:51], 2, v[48:49]
	global_load_dword v212, v[50:51], off
	v_add_u32_e32 v7, s94, v26
	v_mad_u64_u32 v[50:51], s[16:17], v7, s10, 0
	v_ashrrev_i32_e32 v9, 31, v7
	v_mov_b32_e32 v52, v51
	v_mad_u64_u32 v[52:53], s[16:17], v9, s10, v[52:53]
	v_mov_b32_e32 v51, v52
	v_lshl_add_u64 v[50:51], v[50:51], 2, v[48:49]
	global_load_dword v213, v[50:51], off
	v_add_u32_e32 v7, s94, v27
	v_mad_u64_u32 v[50:51], s[16:17], v7, s10, 0
	v_ashrrev_i32_e32 v9, 31, v7
	v_mov_b32_e32 v52, v51
	v_mad_u64_u32 v[52:53], s[16:17], v9, s10, v[52:53]
	v_mov_b32_e32 v51, v52
	v_lshl_add_u64 v[50:51], v[50:51], 2, v[48:49]
	global_load_dword v214, v[50:51], off
	v_add_u32_e32 v7, s94, v28
	v_mad_u64_u32 v[50:51], s[16:17], v7, s10, 0
	v_ashrrev_i32_e32 v9, 31, v7
	v_mov_b32_e32 v52, v51
	v_mad_u64_u32 v[52:53], s[16:17], v9, s10, v[52:53]
	v_mov_b32_e32 v51, v52
	v_lshl_add_u64 v[48:49], v[50:51], 2, v[48:49]
	global_load_dword v215, v[48:49], off
	s_lshl_b64 s[16:17], s[94:95], 1
	s_add_u32 s6, s6, s16
	s_addc_u32 s7, s7, s17
	v_mov_b32_e32 v9, v3
	v_lshl_add_u64 v[48:49], s[6:7], 0, v[8:9]
	v_lshl_add_u64 v[54:55], v[48:49], 0, v[54:55]
	s_waitcnt vmcnt(15)
	ds_write_b32 v47, v200
	s_waitcnt vmcnt(14)
	ds_write_b32 v47, v201 offset:1040
	s_waitcnt vmcnt(13)
	ds_write_b32 v47, v202 offset:2080
	s_waitcnt vmcnt(12)
	ds_write_b32 v47, v203 offset:3120
	s_waitcnt vmcnt(11)
	ds_write_b32 v47, v204 offset:4160
	s_waitcnt vmcnt(10)
	ds_write_b32 v47, v205 offset:5200
	s_waitcnt vmcnt(9)
	ds_write_b32 v47, v206 offset:6240
	s_waitcnt vmcnt(8)
	ds_write_b32 v47, v207 offset:7280
	s_waitcnt vmcnt(7)
	ds_write_b32 v47, v208 offset:8320
	s_waitcnt vmcnt(6)
	ds_write_b32 v47, v209 offset:9360
	s_waitcnt vmcnt(5)
	ds_write_b32 v47, v210 offset:10400
	s_waitcnt vmcnt(4)
	ds_write_b32 v47, v211 offset:11440
	s_waitcnt vmcnt(3)
	ds_write_b32 v47, v212 offset:12480
	s_waitcnt vmcnt(2)
	ds_write_b32 v47, v213 offset:13520
	s_waitcnt vmcnt(1)
	ds_write_b32 v47, v214 offset:14560
	s_waitcnt vmcnt(0)
	ds_write_b32 v47, v215 offset:15600
	s_waitcnt lgkmcnt(0)
	s_barrier
	ds_read2_b32 v[50:51], v29 offset0:65 offset1:73
	ds_read2_b32 v[52:53], v29 offset1:8
	s_waitcnt lgkmcnt(0)
	v_cvt_pk_bf16_f32 v7, v52, v50
	v_or_b32_e32 v50, s90, v30
	global_store_dword v[54:55], v7, off
	v_cvt_pk_bf16_f32 v7, v53, v51
	v_ashrrev_i32_e32 v51, 31, v50
	v_lshlrev_b64 v[50:51], 11, v[50:51]
	v_lshl_add_u64 v[50:51], v[48:49], 0, v[50:51]
	global_store_dword v[50:51], v7, off
	ds_read2_b32 v[50:51], v29 offset0:16 offset1:24
	ds_read2_b32 v[52:53], v29 offset0:81 offset1:89
	v_or_b32_e32 v54, s90, v31
	v_ashrrev_i32_e32 v55, 31, v54
	v_lshlrev_b64 v[54:55], 11, v[54:55]
	v_lshl_add_u64 v[54:55], v[48:49], 0, v[54:55]
	s_waitcnt lgkmcnt(0)
	v_cvt_pk_bf16_f32 v7, v50, v52
	v_or_b32_e32 v50, s90, v32
	global_store_dword v[54:55], v7, off
	v_cvt_pk_bf16_f32 v7, v51, v53
	v_ashrrev_i32_e32 v51, 31, v50
	v_lshlrev_b64 v[50:51], 11, v[50:51]
	v_lshl_add_u64 v[50:51], v[48:49], 0, v[50:51]
	global_store_dword v[50:51], v7, off
	ds_read2_b32 v[50:51], v29 offset0:32 offset1:40
	ds_read2_b32 v[52:53], v29 offset0:97 offset1:105
	v_or_b32_e32 v54, s90, v33
	v_ashrrev_i32_e32 v55, 31, v54
	v_lshlrev_b64 v[54:55], 11, v[54:55]
	v_lshl_add_u64 v[54:55], v[48:49], 0, v[54:55]
	s_waitcnt lgkmcnt(0)
	v_cvt_pk_bf16_f32 v7, v50, v52
	v_add_u32_e32 v50, s90, v34
	global_store_dword v[54:55], v7, off
	v_cvt_pk_bf16_f32 v7, v51, v53
	v_ashrrev_i32_e32 v51, 31, v50
	v_lshlrev_b64 v[50:51], 11, v[50:51]
	v_lshl_add_u64 v[50:51], v[48:49], 0, v[50:51]
	global_store_dword v[50:51], v7, off
	ds_read2_b32 v[50:51], v29 offset0:48 offset1:56
	ds_read2_b32 v[52:53], v29 offset0:113 offset1:121
	v_add_u32_e32 v54, s90, v35
	v_ashrrev_i32_e32 v55, 31, v54
	v_lshlrev_b64 v[54:55], 11, v[54:55]
	v_lshl_add_u64 v[54:55], v[48:49], 0, v[54:55]
	s_waitcnt lgkmcnt(0)
	v_cvt_pk_bf16_f32 v7, v50, v52
	v_add_u32_e32 v50, s90, v36
	global_store_dword v[54:55], v7, off
	v_cvt_pk_bf16_f32 v7, v51, v53
	v_ashrrev_i32_e32 v51, 31, v50
	v_lshlrev_b64 v[50:51], 11, v[50:51]
	v_lshl_add_u64 v[48:49], v[48:49], 0, v[50:51]
	global_store_dword v[48:49], v7, off
